# P5 epilogue: out stores non-temporal (never re-read)
# baseline (speedup 1.0000x reference)
.LBB0_769:
	s_lshr_b32 s25, s34, 4
	s_mul_i32 s36, s25, 0xc00
	s_ashr_i32 s37, s36, 31
	v_lshl_or_b32 v128, s58, 8, v162
	s_lshl_b64 s[36:37], s[36:37], 2
	s_add_u32 s36, s6, s36
	v_ashrrev_i32_e32 v129, 31, v128
	v_lshl_add_u32 v214, s34, 8, v160
	s_addc_u32 s37, s7, s37
	v_lshlrev_b64 v[156:157], 2, v[128:129]
	v_or_b32_e32 v182, 16, v214
	v_lshl_add_u64 v[128:129], s[36:37], 0, v[156:157]
	v_ashrrev_i32_e32 v215, 31, v214
	v_ashrrev_i32_e32 v183, 31, v182
	v_lshl_add_u64 v[130:131], v[128:129], 0, s[14:15]
	v_add_co_u32_e32 v128, vcc, s57, v128
	v_lshl_add_u64 v[158:159], s[10:11], 0, v[156:157]
	v_lshlrev_b64 v[230:231], 12, v[214:215]
	v_lshlrev_b64 v[232:233], 12, v[182:183]
	v_addc_co_u32_e32 v129, vcc, 0, v129, vcc
	v_lshl_add_u64 v[178:179], v[158:159], 0, v[230:231]
	v_lshl_add_u64 v[194:195], v[158:159], 0, v[232:233]
	global_load_dwordx4 v[136:139], v[130:131], off offset:64
	global_load_dwordx4 v[132:135], v[130:131], off offset:512
	global_load_dwordx4 v[140:143], v[128:129], off
	s_nop 0
	global_load_dwordx4 v[128:131], v[130:131], off offset:576
	global_load_dwordx4 v[166:169], v[178:179], off
	global_load_dwordx4 v[170:173], v[178:179], off offset:64
	global_load_dwordx4 v[174:177], v[178:179], off offset:512
	s_nop 0
	global_load_dwordx4 v[178:181], v[178:179], off offset:576
	s_nop 0
	global_load_dwordx4 v[182:185], v[194:195], off
	global_load_dwordx4 v[186:189], v[194:195], off offset:64
	global_load_dwordx4 v[190:193], v[194:195], off offset:512
	s_nop 0
	global_load_dwordx4 v[194:197], v[194:195], off offset:576
	v_or_b32_e32 v198, 32, v214
	v_or_b32_e32 v214, 48, v214
	v_ashrrev_i32_e32 v199, 31, v198
	v_ashrrev_i32_e32 v215, 31, v214
	v_lshlrev_b64 v[234:235], 12, v[198:199]
	v_lshlrev_b64 v[236:237], 12, v[214:215]
	v_lshl_add_u64 v[210:211], v[158:159], 0, v[234:235]
	v_lshl_add_u64 v[226:227], v[158:159], 0, v[236:237]
	global_load_dwordx4 v[198:201], v[210:211], off
	global_load_dwordx4 v[202:205], v[210:211], off offset:64
	global_load_dwordx4 v[206:209], v[210:211], off offset:512
	s_nop 0
	global_load_dwordx4 v[210:213], v[210:211], off offset:576
	s_nop 0
	global_load_dwordx4 v[214:217], v[226:227], off
	global_load_dwordx4 v[218:221], v[226:227], off offset:64
	global_load_dwordx4 v[222:225], v[226:227], off offset:512
	s_nop 0
	global_load_dwordx4 v[226:229], v[226:227], off offset:576
	s_waitcnt vmcnt(15)
	v_pk_fma_f32 v[124:125], v[124:125], v[140:141], v[166:167]
	v_lshl_add_u64 v[166:167], s[4:5], 0, v[230:231]
	v_lshl_add_u64 v[166:167], v[166:167], 0, v[156:157]
	s_waitcnt vmcnt(13)
	v_pk_fma_f32 v[114:115], v[114:115], v[134:135], v[176:177]
	v_pk_fma_f32 v[112:113], v[112:113], v[132:133], v[174:175]
	global_store_dwordx4 v[166:167], v[112:115], off offset:512 nt
	s_waitcnt vmcnt(13)
	v_pk_fma_f32 v[106:107], v[106:107], v[130:131], v[180:181]
	v_pk_fma_f32 v[104:105], v[104:105], v[128:129], v[178:179]
	v_lshl_add_u64 v[112:113], s[4:5], 0, v[232:233]
	global_store_dwordx4 v[166:167], v[104:107], off offset:576 nt
	v_lshl_add_u64 v[112:113], v[112:113], 0, v[156:157]
	v_pk_fma_f32 v[126:127], v[126:127], v[142:143], v[168:169]
	s_waitcnt vmcnt(13)
	v_pk_fma_f32 v[106:107], v[118:119], v[142:143], v[184:185]
	v_pk_fma_f32 v[104:105], v[116:117], v[140:141], v[182:183]
	v_pk_fma_f32 v[122:123], v[122:123], v[138:139], v[172:173]
	v_pk_fma_f32 v[120:121], v[120:121], v[136:137], v[170:171]
	global_store_dwordx4 v[112:113], v[104:107], off nt
	s_waitcnt vmcnt(12)
	v_pk_fma_f32 v[102:103], v[102:103], v[134:135], v[192:193]
	v_pk_fma_f32 v[100:101], v[100:101], v[132:133], v[190:191]
	v_pk_fma_f32 v[106:107], v[110:111], v[138:139], v[188:189]
	v_pk_fma_f32 v[104:105], v[108:109], v[136:137], v[186:187]
	s_waitcnt vmcnt(11)
	v_pk_fma_f32 v[94:95], v[94:95], v[130:131], v[196:197]
	v_pk_fma_f32 v[92:93], v[92:93], v[128:129], v[194:195]
	global_store_dwordx4 v[166:167], v[124:127], off nt
	global_store_dwordx4 v[166:167], v[120:123], off offset:64 nt
	global_store_dwordx4 v[112:113], v[104:107], off offset:64 nt
	global_store_dwordx4 v[112:113], v[100:103], off offset:512 nt
	global_store_dwordx4 v[112:113], v[92:95], off offset:576 nt
	v_lshl_add_u64 v[166:167], v[230:231], 0, s[16:17]
	v_lshl_add_u64 v[168:169], v[230:231], 0, s[18:19]
	v_lshl_add_u64 v[108:109], v[158:159], 0, v[166:167]
	v_lshl_add_u64 v[124:125], v[158:159], 0, v[168:169]
	global_load_dwordx4 v[92:95], v[108:109], off
	global_load_dwordx4 v[100:103], v[108:109], off offset:64
	global_load_dwordx4 v[104:107], v[108:109], off offset:512
	s_nop 0
	global_load_dwordx4 v[108:111], v[108:109], off offset:576
	s_nop 0
	global_load_dwordx4 v[112:115], v[124:125], off
	global_load_dwordx4 v[116:119], v[124:125], off offset:64
	global_load_dwordx4 v[120:123], v[124:125], off offset:512
	s_nop 0
	global_load_dwordx4 v[124:127], v[124:125], off offset:576
	v_lshl_add_u64 v[170:171], s[4:5], 0, v[234:235]
	v_lshl_add_u64 v[170:171], v[170:171], 0, v[156:157]
	s_waitcnt vmcnt(21)
	v_pk_fma_f32 v[82:83], v[82:83], v[134:135], v[208:209]
	v_pk_fma_f32 v[80:81], v[80:81], v[132:133], v[206:207]
	global_store_dwordx4 v[170:171], v[80:83], off offset:512 nt
	s_waitcnt vmcnt(21)
	v_pk_fma_f32 v[74:75], v[74:75], v[130:131], v[212:213]
	v_pk_fma_f32 v[72:73], v[72:73], v[128:129], v[210:211]
	v_lshl_add_u64 v[80:81], s[4:5], 0, v[236:237]
	global_store_dwordx4 v[170:171], v[72:75], off offset:576 nt
	v_lshl_add_u64 v[80:81], v[80:81], 0, v[156:157]
	v_pk_fma_f32 v[98:99], v[98:99], v[142:143], v[200:201]
	s_waitcnt vmcnt(21)
	v_pk_fma_f32 v[74:75], v[86:87], v[142:143], v[216:217]
	v_pk_fma_f32 v[72:73], v[84:85], v[140:141], v[214:215]
	v_pk_fma_f32 v[96:97], v[96:97], v[140:141], v[198:199]
	v_pk_fma_f32 v[90:91], v[90:91], v[138:139], v[204:205]
	v_pk_fma_f32 v[88:89], v[88:89], v[136:137], v[202:203]
	global_store_dwordx4 v[80:81], v[72:75], off nt
	s_waitcnt vmcnt(20)
	v_pk_fma_f32 v[70:71], v[70:71], v[134:135], v[224:225]
	v_pk_fma_f32 v[68:69], v[68:69], v[132:133], v[222:223]
	v_pk_fma_f32 v[74:75], v[78:79], v[138:139], v[220:221]
	v_pk_fma_f32 v[72:73], v[76:77], v[136:137], v[218:219]
	s_waitcnt vmcnt(19)
	v_pk_fma_f32 v[66:67], v[66:67], v[130:131], v[228:229]
	v_pk_fma_f32 v[64:65], v[64:65], v[128:129], v[226:227]
	global_store_dwordx4 v[170:171], v[96:99], off nt
	global_store_dwordx4 v[170:171], v[88:91], off offset:64 nt
	global_store_dwordx4 v[80:81], v[72:75], off offset:64 nt
	global_store_dwordx4 v[80:81], v[68:71], off offset:512 nt
	global_store_dwordx4 v[80:81], v[64:67], off offset:576 nt
	v_lshl_add_u64 v[170:171], v[230:231], 0, s[20:21]
	v_lshl_add_u64 v[172:173], v[230:231], 0, s[22:23]
	v_lshl_add_u64 v[76:77], v[158:159], 0, v[170:171]
	v_lshl_add_u64 v[96:97], v[158:159], 0, v[172:173]
	global_load_dwordx4 v[64:67], v[76:77], off
	global_load_dwordx4 v[68:71], v[76:77], off offset:64
	global_load_dwordx4 v[72:75], v[76:77], off offset:512
	s_nop 0
	global_load_dwordx4 v[76:79], v[76:77], off offset:576
	s_nop 0
	global_load_dwordx4 v[80:83], v[96:97], off
	global_load_dwordx4 v[84:87], v[96:97], off offset:64
	global_load_dwordx4 v[88:91], v[96:97], off offset:512
	s_nop 0
	global_load_dwordx4 v[96:99], v[96:97], off offset:576
	s_waitcnt vmcnt(23)
	v_pk_fma_f32 v[60:61], v[60:61], v[140:141], v[92:93]
	v_lshl_add_u64 v[92:93], s[4:5], 0, v[166:167]
	v_lshl_add_u64 v[92:93], v[92:93], 0, v[156:157]
	s_waitcnt vmcnt(21)
	v_pk_fma_f32 v[50:51], v[50:51], v[134:135], v[106:107]
	v_pk_fma_f32 v[48:49], v[48:49], v[132:133], v[104:105]
	global_store_dwordx4 v[92:93], v[48:51], off offset:512 nt
	s_waitcnt vmcnt(18)
	v_pk_fma_f32 v[34:35], v[34:35], v[134:135], v[122:123]
	v_pk_fma_f32 v[32:33], v[32:33], v[132:133], v[120:121]
	v_lshl_add_u64 v[48:49], s[4:5], 0, v[168:169]
	v_lshl_add_u64 v[48:49], v[48:49], 0, v[156:157]
	global_store_dwordx4 v[48:49], v[32:35], off offset:512 nt
	s_waitcnt vmcnt(7)
	v_pk_fma_f32 v[18:19], v[18:19], v[134:135], v[74:75]
	v_pk_fma_f32 v[16:17], v[16:17], v[132:133], v[72:73]
	v_lshl_add_u64 v[32:33], s[4:5], 0, v[170:171]
	v_lshl_add_u64 v[32:33], v[32:33], 0, v[156:157]
	v_pk_fma_f32 v[42:43], v[42:43], v[130:131], v[110:111]
	v_pk_fma_f32 v[40:41], v[40:41], v[128:129], v[108:109]
	v_pk_fma_f32 v[26:27], v[26:27], v[130:131], v[126:127]
	v_pk_fma_f32 v[24:25], v[24:25], v[128:129], v[124:125]
	global_store_dwordx4 v[32:33], v[16:19], off offset:512 nt
	s_waitcnt vmcnt(7)
	v_pk_fma_f32 v[10:11], v[10:11], v[130:131], v[78:79]
	v_pk_fma_f32 v[8:9], v[8:9], v[128:129], v[76:77]
	v_lshl_add_u64 v[16:17], s[4:5], 0, v[172:173]
	global_store_dwordx4 v[92:93], v[40:43], off offset:576 nt
	global_store_dwordx4 v[48:49], v[24:27], off offset:576 nt
	global_store_dwordx4 v[32:33], v[8:11], off offset:576 nt
	v_pk_fma_f32 v[42:43], v[54:55], v[142:143], v[114:115]
	v_pk_fma_f32 v[40:41], v[52:53], v[140:141], v[112:113]
	v_pk_fma_f32 v[26:27], v[38:39], v[142:143], v[66:67]
	v_pk_fma_f32 v[24:25], v[36:37], v[140:141], v[64:65]
	s_waitcnt vmcnt(9)
	v_pk_fma_f32 v[10:11], v[22:23], v[142:143], v[82:83]
	v_pk_fma_f32 v[8:9], v[20:21], v[140:141], v[80:81]
	v_lshl_add_u64 v[16:17], v[16:17], 0, v[156:157]
	v_pk_fma_f32 v[62:63], v[62:63], v[142:143], v[94:95]
	v_pk_fma_f32 v[58:59], v[58:59], v[138:139], v[102:103]
	v_pk_fma_f32 v[56:57], v[56:57], v[136:137], v[100:101]
	global_store_dwordx4 v[48:49], v[40:43], off nt
	global_store_dwordx4 v[32:33], v[24:27], off nt
	global_store_dwordx4 v[16:17], v[8:11], off nt
	v_pk_fma_f32 v[42:43], v[46:47], v[138:139], v[118:119]
	v_pk_fma_f32 v[40:41], v[44:45], v[136:137], v[116:117]
	v_pk_fma_f32 v[26:27], v[30:31], v[138:139], v[70:71]
	v_pk_fma_f32 v[24:25], v[28:29], v[136:137], v[68:69]
	s_waitcnt vmcnt(11)
	v_pk_fma_f32 v[10:11], v[14:15], v[138:139], v[86:87]
	v_pk_fma_f32 v[8:9], v[12:13], v[136:137], v[84:85]
	s_waitcnt vmcnt(10)
	v_pk_fma_f32 v[6:7], v[6:7], v[134:135], v[90:91]
	v_pk_fma_f32 v[4:5], v[4:5], v[132:133], v[88:89]
	s_waitcnt vmcnt(9)
	v_pk_fma_f32 v[2:3], v[2:3], v[130:131], v[98:99]
	v_pk_fma_f32 v[0:1], v[0:1], v[128:129], v[96:97]
	global_store_dwordx4 v[92:93], v[60:63], off nt
	global_store_dwordx4 v[92:93], v[56:59], off offset:64 nt
	global_store_dwordx4 v[48:49], v[40:43], off offset:64 nt
	global_store_dwordx4 v[32:33], v[24:27], off offset:64 nt
	global_store_dwordx4 v[16:17], v[8:11], off offset:64 nt
	global_store_dwordx4 v[16:17], v[4:7], off offset:512 nt
	global_store_dwordx4 v[16:17], v[0:3], off offset:576 nt
	s_andn2_b64 vcc, exec, s[0:1]
	s_mov_b64 s[0:1], -1
	s_cbranch_vccnz .LBB0_758
	s_andn2_b64 vcc, exec, s[2:3]
	s_cbranch_vccnz .LBB0_757
	s_barrier
	s_branch .LBB0_757
